# FFN-down and w_out GEMM epilogues: residual / gain fragment loads issued at the top of the epilogue, counted waits instead of drains
# speedup vs baseline: 1.0220x; 1.0151x over previous
.LBB0_1803:
	v_lshl_add_u32 v150, s24, 8, v158
	v_lshl_or_b32 v148, s42, 8, v160
	v_ashrrev_i32_e32 v151, 31, v150
	v_ashrrev_i32_e32 v149, 31, v148
	v_lshlrev_b64 v[152:153], 11, v[150:151]
	v_lshl_add_u64 v[152:153], v[152:153], 0, v[148:149]
	v_readlane_b32 s52, v251, 8
	v_lshlrev_b64 v[154:155], 1, v[152:153]
	v_readlane_b32 s56, v251, 12
	v_readlane_b32 s57, v251, 13
	v_readlane_b32 s24, v251, 16
	v_readlane_b32 s53, v251, 9
	v_lshl_add_u64 v[156:157], s[56:57], 0, v[154:155]
	v_readlane_b32 s54, v251, 10
	v_readlane_b32 s55, v251, 11
	v_readlane_b32 s58, v251, 14
	v_readlane_b32 s59, v251, 15
	v_cndmask_b32_e64 v168, 0, 1, s[20:21]
	v_readlane_b32 s25, v251, 17
	v_cmp_ne_u32_e64 s[42:43], 1, v168
	v_readlane_b32 s52, v251, 49
	v_lshl_add_u64 v[168:169], s[24:25], 0, v[154:155]
	v_readlane_b32 s62, v251, 59
	v_readlane_b32 s63, v251, 60
	s_andn2_b64 vcc, exec, s[20:21]
	v_readlane_b32 s53, v251, 50
	v_readlane_b32 s54, v251, 51
	v_readlane_b32 s55, v251, 52
	v_readlane_b32 s56, v251, 53
	v_readlane_b32 s57, v251, 54
	v_readlane_b32 s58, v251, 55
	v_readlane_b32 s59, v251, 56
	v_readlane_b32 s60, v251, 57
	v_readlane_b32 s61, v251, 58
	v_readlane_b32 s64, v251, 61
	v_readlane_b32 s65, v251, 62
	v_readlane_b32 s66, v251, 63
	v_readlane_b32 s67, v252, 0
	v_mov_b32_e32 v246, 0x10000
	v_mov_b32_e32 v247, 0
	s_cbranch_vccnz .Lp6e_nog
	v_lshl_add_u64 v[244:245], v[148:149], 2, s[62:63]
	global_load_dwordx4 v[228:231], v[244:245], off
	global_load_dwordx4 v[232:235], v[244:245], off offset:16
	global_load_dwordx4 v[236:239], v[244:245], off offset:512
	global_load_dwordx4 v[240:243], v[244:245], off offset:528
.Lp6e_nog:
	v_mov_b32_e32 v244, v156
	v_mov_b32_e32 v245, v157
	global_load_dwordx4 v[178:181], v[244:245], off
	global_load_dwordx4 v[182:185], v[244:245], off offset:256
	v_lshl_add_u64 v[244:245], v[244:245], 0, v[246:247]
	global_load_dwordx4 v[186:189], v[244:245], off
	global_load_dwordx4 v[192:195], v[244:245], off offset:256
	v_lshl_add_u64 v[244:245], v[244:245], 0, v[246:247]
	global_load_dwordx4 v[196:199], v[244:245], off
	global_load_dwordx4 v[200:203], v[244:245], off offset:256
	v_lshl_add_u64 v[244:245], v[244:245], 0, v[246:247]
	global_load_dwordx4 v[204:207], v[244:245], off
	global_load_dwordx4 v[208:211], v[244:245], off offset:256
	v_lshl_add_u64 v[244:245], v[244:245], 0, v[246:247]
	v_lshl_add_u64 v[244:245], v[244:245], 0, v[246:247]
	v_lshl_add_u64 v[244:245], v[244:245], 0, v[246:247]
	v_lshl_add_u64 v[244:245], v[244:245], 0, v[246:247]
	v_lshl_add_u64 v[244:245], v[244:245], 0, v[246:247]
	global_load_dwordx4 v[212:215], v[244:245], off
	global_load_dwordx4 v[216:219], v[244:245], off offset:256
	v_lshl_add_u64 v[244:245], v[244:245], 0, v[246:247]
	global_load_dwordx4 v[220:223], v[244:245], off
	global_load_dwordx4 v[224:227], v[244:245], off offset:256
	v_lshl_add_u64 v[244:245], v[244:245], 0, v[246:247]
	s_waitcnt vmcnt(11)
	s_nop 1
	v_mov_b32_e32 v164, v178
	v_mov_b32_e32 v165, v179
	v_mov_b32_e32 v166, v180
	v_mov_b32_e32 v167, v181
	global_load_dwordx4 v[178:181], v[244:245], off
	v_lshlrev_b32_e32 v154, 16, v164
	v_and_b32_e32 v155, 0xffff0000, v164
	v_lshlrev_b32_e32 v164, 16, v165
	v_and_b32_e32 v165, 0xffff0000, v165
	v_lshlrev_b32_e32 v174, 16, v166
	v_and_b32_e32 v175, 0xffff0000, v166
	v_lshlrev_b32_e32 v166, 16, v167
	v_and_b32_e32 v167, 0xffff0000, v167
	v_pk_add_f32 v[126:127], v[126:127], v[164:165]
	v_pk_add_f32 v[154:155], v[124:125], v[154:155]
	v_pk_add_f32 v[122:123], v[122:123], v[166:167]
	v_pk_add_f32 v[124:125], v[120:121], v[174:175]
	v_cvt_pk_bf16_f32 v164, v154, v155
	v_cvt_pk_bf16_f32 v165, v126, v127
	v_cvt_pk_bf16_f32 v166, v124, v125
	v_cvt_pk_bf16_f32 v167, v122, v123
	v_lshl_add_u64 v[120:121], v[148:149], 2, s[62:63]
	global_store_dwordx4 v[168:169], v[164:167], off
	s_cbranch_vccnz .LBB0_1805
	s_nop 3
	v_mov_b32_e32 v164, v228
	v_mov_b32_e32 v165, v229
	v_mov_b32_e32 v166, v230
	v_mov_b32_e32 v167, v231
	v_mov_b32_e32 v174, v232
	v_mov_b32_e32 v175, v233
	v_mov_b32_e32 v176, v234
	v_mov_b32_e32 v177, v235
	v_pk_mul_f32 v[166:167], v[126:127], v[166:167]
	v_pk_mul_f32 v[164:165], v[154:155], v[164:165]
	v_pk_mul_f32 v[168:169], v[122:123], v[176:177]
	v_pk_mul_f32 v[174:175], v[124:125], v[174:175]
	v_cvt_pk_bf16_f32 v164, v164, v165
	v_cvt_pk_bf16_f32 v165, v166, v167
	v_cvt_pk_bf16_f32 v166, v174, v175
	v_cvt_pk_bf16_f32 v167, v168, v169
	v_lshl_add_u64 v[168:169], v[152:153], 1, s[6:7]
	global_store_dwordx4 v[168:169], v[164:167], off
.LBB0_1805:
	v_readlane_b32 s24, v251, 16
	v_or_b32_e32 v152, 0x80, v152
	v_readlane_b32 s25, v251, 17
	s_and_b64 vcc, exec, s[42:43]
	s_waitcnt vmcnt(12)
	s_nop 1
	v_mov_b32_e32 v164, v182
	v_mov_b32_e32 v165, v183
	v_mov_b32_e32 v166, v184
	v_mov_b32_e32 v167, v185
	global_load_dwordx4 v[182:185], v[244:245], off offset:256
	v_lshl_add_u64 v[244:245], v[244:245], 0, v[246:247]
	v_lshlrev_b32_e32 v156, 16, v164
	v_and_b32_e32 v157, 0xffff0000, v164
	v_lshlrev_b32_e32 v164, 16, v165
	v_and_b32_e32 v165, 0xffff0000, v165
	v_lshlrev_b32_e32 v168, 16, v166
	v_and_b32_e32 v169, 0xffff0000, v166
	v_lshlrev_b32_e32 v166, 16, v167
	v_and_b32_e32 v167, 0xffff0000, v167
	v_pk_add_f32 v[118:119], v[118:119], v[164:165]
	v_pk_add_f32 v[116:117], v[116:117], v[156:157]
	v_pk_add_f32 v[114:115], v[114:115], v[166:167]
	v_pk_add_f32 v[112:113], v[112:113], v[168:169]
	v_cvt_pk_bf16_f32 v164, v116, v117
	v_cvt_pk_bf16_f32 v165, v118, v119
	v_cvt_pk_bf16_f32 v166, v112, v113
	v_cvt_pk_bf16_f32 v167, v114, v115
	v_lshl_add_u64 v[156:157], v[152:153], 1, s[24:25]
	global_store_dwordx4 v[156:157], v[164:167], off
	s_cbranch_vccnz .LBB0_1807
	v_lshl_add_u64 v[152:153], v[152:153], 1, s[6:7]
	s_nop 3
	v_mov_b32_e32 v164, v236
	v_mov_b32_e32 v165, v237
	v_mov_b32_e32 v166, v238
	v_mov_b32_e32 v167, v239
	v_mov_b32_e32 v174, v240
	v_mov_b32_e32 v175, v241
	v_mov_b32_e32 v176, v242
	v_mov_b32_e32 v177, v243
	v_pk_mul_f32 v[156:157], v[118:119], v[166:167]
	v_pk_mul_f32 v[164:165], v[116:117], v[164:165]
	v_pk_mul_f32 v[168:169], v[114:115], v[176:177]
	v_pk_mul_f32 v[166:167], v[112:113], v[174:175]
	v_cvt_pk_bf16_f32 v164, v164, v165
	v_cvt_pk_bf16_f32 v165, v156, v157
	v_cvt_pk_bf16_f32 v166, v166, v167
	v_cvt_pk_bf16_f32 v167, v168, v169
	global_store_dwordx4 v[152:153], v[164:167], off

.LBB0_1809:
	s_or_b64 exec, exec, s[24:25]
	v_or_b32_e32 v112, 16, v150
	s_waitcnt lgkmcnt(0)
	v_ashrrev_i32_e32 v113, 31, v112
	v_lshlrev_b64 v[114:115], 11, v[112:113]
	v_lshl_add_u64 v[114:115], v[114:115], 0, v[148:149]
	v_readlane_b32 s52, v251, 8
	v_lshlrev_b64 v[126:127], 1, v[114:115]
	v_readlane_b32 s56, v251, 12
	v_readlane_b32 s57, v251, 13
	v_readlane_b32 s24, v251, 16
	v_readlane_b32 s25, v251, 17
	v_lshl_add_u64 v[116:117], s[56:57], 0, v[126:127]
	v_lshl_add_u64 v[126:127], s[24:25], 0, v[126:127]
	s_and_b64 vcc, exec, s[42:43]
	v_readlane_b32 s53, v251, 9
	v_readlane_b32 s54, v251, 10
	v_readlane_b32 s55, v251, 11
	v_readlane_b32 s58, v251, 14
	v_readlane_b32 s59, v251, 15
	s_waitcnt vmcnt(13)
	s_nop 1
	v_mov_b32_e32 v122, v186
	v_mov_b32_e32 v123, v187
	v_mov_b32_e32 v124, v188
	v_mov_b32_e32 v125, v189
	global_load_dwordx4 v[186:189], v[244:245], off
	v_lshlrev_b32_e32 v152, 16, v122
	v_and_b32_e32 v153, 0xffff0000, v122
	v_lshlrev_b32_e32 v122, 16, v123
	v_and_b32_e32 v123, 0xffff0000, v123
	v_lshlrev_b32_e32 v154, 16, v124
	v_and_b32_e32 v155, 0xffff0000, v124
	v_lshlrev_b32_e32 v124, 16, v125
	v_and_b32_e32 v125, 0xffff0000, v125
	v_pk_add_f32 v[110:111], v[110:111], v[122:123]
	v_pk_add_f32 v[108:109], v[108:109], v[152:153]
	v_pk_add_f32 v[106:107], v[106:107], v[124:125]
	v_pk_add_f32 v[104:105], v[104:105], v[154:155]
	v_cvt_pk_bf16_f32 v122, v108, v109
	v_cvt_pk_bf16_f32 v123, v110, v111
	v_cvt_pk_bf16_f32 v124, v104, v105
	v_cvt_pk_bf16_f32 v125, v106, v107
	global_store_dwordx4 v[126:127], v[122:125], off
	s_cbranch_vccnz .LBB0_1811
	s_nop 3
	v_mov_b32_e32 v122, v228
	v_mov_b32_e32 v123, v229
	v_mov_b32_e32 v124, v230
	v_mov_b32_e32 v125, v231
	v_mov_b32_e32 v152, v232
	v_mov_b32_e32 v153, v233
	v_mov_b32_e32 v154, v234
	v_mov_b32_e32 v155, v235
	v_pk_mul_f32 v[124:125], v[110:111], v[124:125]
	v_pk_mul_f32 v[122:123], v[108:109], v[122:123]
	v_pk_mul_f32 v[126:127], v[106:107], v[154:155]
	v_pk_mul_f32 v[152:153], v[104:105], v[152:153]
	v_cvt_pk_bf16_f32 v122, v122, v123
	v_cvt_pk_bf16_f32 v123, v124, v125
	v_cvt_pk_bf16_f32 v124, v152, v153
	v_cvt_pk_bf16_f32 v125, v126, v127
	v_lshl_add_u64 v[126:127], v[114:115], 1, s[6:7]
	global_store_dwordx4 v[126:127], v[122:125], off
.LBB0_1811:
	v_readlane_b32 s24, v251, 16
	v_or_b32_e32 v114, 0x80, v114
	v_readlane_b32 s25, v251, 17
	s_and_b64 vcc, exec, s[42:43]
	s_waitcnt vmcnt(14)
	s_nop 1
	v_mov_b32_e32 v122, v192
	v_mov_b32_e32 v123, v193
	v_mov_b32_e32 v124, v194
	v_mov_b32_e32 v125, v195
	global_load_dwordx4 v[192:195], v[244:245], off offset:256
	v_lshlrev_b32_e32 v116, 16, v122
	v_and_b32_e32 v117, 0xffff0000, v122
	v_lshlrev_b32_e32 v122, 16, v123
	v_and_b32_e32 v123, 0xffff0000, v123
	v_lshlrev_b32_e32 v126, 16, v124
	v_and_b32_e32 v127, 0xffff0000, v124
	v_lshlrev_b32_e32 v124, 16, v125
	v_and_b32_e32 v125, 0xffff0000, v125
	v_pk_add_f32 v[102:103], v[102:103], v[122:123]
	v_pk_add_f32 v[100:101], v[100:101], v[116:117]
	v_pk_add_f32 v[98:99], v[98:99], v[124:125]
	v_pk_add_f32 v[96:97], v[96:97], v[126:127]
	v_cvt_pk_bf16_f32 v122, v100, v101
	v_cvt_pk_bf16_f32 v123, v102, v103
	v_cvt_pk_bf16_f32 v124, v96, v97
	v_cvt_pk_bf16_f32 v125, v98, v99
	v_lshl_add_u64 v[116:117], v[114:115], 1, s[24:25]
	global_store_dwordx4 v[116:117], v[122:125], off
	s_cbranch_vccnz .LBB0_1813
	v_lshl_add_u64 v[114:115], v[114:115], 1, s[6:7]
	s_nop 3
	v_mov_b32_e32 v122, v236
	v_mov_b32_e32 v123, v237
	v_mov_b32_e32 v124, v238
	v_mov_b32_e32 v125, v239
	v_mov_b32_e32 v152, v240
	v_mov_b32_e32 v153, v241
	v_mov_b32_e32 v154, v242
	v_mov_b32_e32 v155, v243
	v_pk_mul_f32 v[116:117], v[102:103], v[124:125]
	v_pk_mul_f32 v[122:123], v[100:101], v[122:123]
	v_pk_mul_f32 v[126:127], v[98:99], v[154:155]
	v_pk_mul_f32 v[124:125], v[96:97], v[152:153]
	v_cvt_pk_bf16_f32 v122, v122, v123
	v_cvt_pk_bf16_f32 v123, v116, v117
	v_cvt_pk_bf16_f32 v124, v124, v125
	v_cvt_pk_bf16_f32 v125, v126, v127
	global_store_dwordx4 v[114:115], v[122:125], off

.LBB0_1815:
	s_or_b64 exec, exec, s[24:25]
	v_or_b32_e32 v96, 32, v150
	s_waitcnt lgkmcnt(0)
	v_ashrrev_i32_e32 v97, 31, v96
	v_lshlrev_b64 v[98:99], 11, v[96:97]
	v_lshl_add_u64 v[98:99], v[98:99], 0, v[148:149]
	v_readlane_b32 s52, v251, 8
	v_lshlrev_b64 v[106:107], 1, v[98:99]
	v_readlane_b32 s56, v251, 12
	v_readlane_b32 s57, v251, 13
	v_readlane_b32 s24, v251, 16
	v_readlane_b32 s25, v251, 17
	v_lshl_add_u64 v[100:101], s[56:57], 0, v[106:107]
	v_lshl_add_u64 v[106:107], s[24:25], 0, v[106:107]
	s_and_b64 vcc, exec, s[42:43]
	v_readlane_b32 s53, v251, 9
	v_readlane_b32 s54, v251, 10
	v_readlane_b32 s55, v251, 11
	v_readlane_b32 s58, v251, 14
	v_readlane_b32 s59, v251, 15
	s_waitcnt vmcnt(15)
	s_nop 1
	v_mov_b32_e32 v102, v196
	v_mov_b32_e32 v103, v197
	v_mov_b32_e32 v104, v198
	v_mov_b32_e32 v105, v199
	v_lshlrev_b32_e32 v108, 16, v102
	v_and_b32_e32 v109, 0xffff0000, v102
	v_lshlrev_b32_e32 v102, 16, v103
	v_and_b32_e32 v103, 0xffff0000, v103
	v_lshlrev_b32_e32 v110, 16, v104
	v_and_b32_e32 v111, 0xffff0000, v104
	v_lshlrev_b32_e32 v104, 16, v105
	v_and_b32_e32 v105, 0xffff0000, v105
	v_pk_add_f32 v[94:95], v[94:95], v[102:103]
	v_pk_add_f32 v[92:93], v[92:93], v[108:109]
	v_pk_add_f32 v[90:91], v[90:91], v[104:105]
	v_pk_add_f32 v[88:89], v[88:89], v[110:111]
	v_cvt_pk_bf16_f32 v102, v92, v93
	v_cvt_pk_bf16_f32 v103, v94, v95
	v_cvt_pk_bf16_f32 v104, v88, v89
	v_cvt_pk_bf16_f32 v105, v90, v91
	global_store_dwordx4 v[106:107], v[102:105], off
	s_cbranch_vccnz .LBB0_1817
	s_nop 3
	v_mov_b32_e32 v102, v228
	v_mov_b32_e32 v103, v229
	v_mov_b32_e32 v104, v230
	v_mov_b32_e32 v105, v231
	v_mov_b32_e32 v106, v232
	v_mov_b32_e32 v107, v233
	v_mov_b32_e32 v108, v234
	v_mov_b32_e32 v109, v235
	v_pk_mul_f32 v[104:105], v[94:95], v[104:105]
	v_pk_mul_f32 v[102:103], v[92:93], v[102:103]
	v_pk_mul_f32 v[108:109], v[90:91], v[108:109]
	v_pk_mul_f32 v[106:107], v[88:89], v[106:107]
	v_cvt_pk_bf16_f32 v102, v102, v103
	v_cvt_pk_bf16_f32 v103, v104, v105
	v_cvt_pk_bf16_f32 v104, v106, v107
	v_cvt_pk_bf16_f32 v105, v108, v109
	v_lshl_add_u64 v[106:107], v[98:99], 1, s[6:7]
	global_store_dwordx4 v[106:107], v[102:105], off
.LBB0_1817:
	v_readlane_b32 s24, v251, 16
	v_or_b32_e32 v98, 0x80, v98
	v_readlane_b32 s25, v251, 17
	s_and_b64 vcc, exec, s[42:43]
	s_waitcnt vmcnt(15)
	s_nop 1
	v_mov_b32_e32 v100, v200
	v_mov_b32_e32 v101, v201
	v_mov_b32_e32 v102, v202
	v_mov_b32_e32 v103, v203
	v_lshlrev_b32_e32 v104, 16, v100
	v_and_b32_e32 v105, 0xffff0000, v100
	v_lshlrev_b32_e32 v100, 16, v101
	v_and_b32_e32 v101, 0xffff0000, v101
	v_lshlrev_b32_e32 v106, 16, v102
	v_and_b32_e32 v107, 0xffff0000, v102
	v_lshlrev_b32_e32 v102, 16, v103
	v_and_b32_e32 v103, 0xffff0000, v103
	v_pk_add_f32 v[86:87], v[86:87], v[100:101]
	v_pk_add_f32 v[84:85], v[84:85], v[104:105]
	v_pk_add_f32 v[82:83], v[82:83], v[102:103]
	v_pk_add_f32 v[80:81], v[80:81], v[106:107]
	v_cvt_pk_bf16_f32 v100, v84, v85
	v_cvt_pk_bf16_f32 v101, v86, v87
	v_cvt_pk_bf16_f32 v102, v80, v81
	v_cvt_pk_bf16_f32 v103, v82, v83
	v_lshl_add_u64 v[104:105], v[98:99], 1, s[24:25]
	global_store_dwordx4 v[104:105], v[100:103], off
	s_cbranch_vccnz .LBB0_1819
	v_lshl_add_u64 v[98:99], v[98:99], 1, s[6:7]
	s_nop 3
	v_mov_b32_e32 v100, v236
	v_mov_b32_e32 v101, v237
	v_mov_b32_e32 v102, v238
	v_mov_b32_e32 v103, v239
	v_mov_b32_e32 v104, v240
	v_mov_b32_e32 v105, v241
	v_mov_b32_e32 v106, v242
	v_mov_b32_e32 v107, v243
	v_pk_mul_f32 v[102:103], v[86:87], v[102:103]
	v_pk_mul_f32 v[100:101], v[84:85], v[100:101]
	v_pk_mul_f32 v[106:107], v[82:83], v[106:107]
	v_pk_mul_f32 v[104:105], v[80:81], v[104:105]
	v_cvt_pk_bf16_f32 v100, v100, v101
	v_cvt_pk_bf16_f32 v101, v102, v103
	v_cvt_pk_bf16_f32 v102, v104, v105
	v_cvt_pk_bf16_f32 v103, v106, v107
	global_store_dwordx4 v[98:99], v[100:103], off

.LBB0_1821:
	s_or_b64 exec, exec, s[24:25]
	v_or_b32_e32 v80, 48, v150
	s_waitcnt lgkmcnt(0)
	v_ashrrev_i32_e32 v81, 31, v80
	v_lshlrev_b64 v[82:83], 11, v[80:81]
	v_lshl_add_u64 v[82:83], v[82:83], 0, v[148:149]
	v_readlane_b32 s52, v251, 8
	v_lshlrev_b64 v[90:91], 1, v[82:83]
	v_readlane_b32 s56, v251, 12
	v_readlane_b32 s57, v251, 13
	v_readlane_b32 s24, v251, 16
	v_readlane_b32 s25, v251, 17
	v_lshl_add_u64 v[84:85], s[56:57], 0, v[90:91]
	v_lshl_add_u64 v[90:91], s[24:25], 0, v[90:91]
	s_and_b64 vcc, exec, s[42:43]
	v_readlane_b32 s53, v251, 9
	v_readlane_b32 s54, v251, 10
	v_readlane_b32 s55, v251, 11
	v_readlane_b32 s58, v251, 14
	v_readlane_b32 s59, v251, 15
	s_waitcnt vmcnt(15)
	s_nop 1
	v_mov_b32_e32 v86, v204
	v_mov_b32_e32 v87, v205
	v_mov_b32_e32 v88, v206
	v_mov_b32_e32 v89, v207
	v_lshlrev_b32_e32 v92, 16, v86
	v_and_b32_e32 v93, 0xffff0000, v86
	v_lshlrev_b32_e32 v86, 16, v87
	v_and_b32_e32 v87, 0xffff0000, v87
	v_lshlrev_b32_e32 v94, 16, v88
	v_and_b32_e32 v95, 0xffff0000, v88
	v_lshlrev_b32_e32 v88, 16, v89
	v_and_b32_e32 v89, 0xffff0000, v89
	v_pk_add_f32 v[78:79], v[78:79], v[86:87]
	v_pk_add_f32 v[76:77], v[76:77], v[92:93]
	v_pk_add_f32 v[74:75], v[74:75], v[88:89]
	v_pk_add_f32 v[72:73], v[72:73], v[94:95]
	v_cvt_pk_bf16_f32 v86, v76, v77
	v_cvt_pk_bf16_f32 v87, v78, v79
	v_cvt_pk_bf16_f32 v88, v72, v73
	v_cvt_pk_bf16_f32 v89, v74, v75
	global_store_dwordx4 v[90:91], v[86:89], off
	s_cbranch_vccnz .LBB0_1823
	s_nop 3
	v_mov_b32_e32 v86, v228
	v_mov_b32_e32 v87, v229
	v_mov_b32_e32 v88, v230
	v_mov_b32_e32 v89, v231
	v_mov_b32_e32 v90, v232
	v_mov_b32_e32 v91, v233
	v_mov_b32_e32 v92, v234
	v_mov_b32_e32 v93, v235
	v_pk_mul_f32 v[88:89], v[78:79], v[88:89]
	v_pk_mul_f32 v[86:87], v[76:77], v[86:87]
	v_pk_mul_f32 v[92:93], v[74:75], v[92:93]
	v_pk_mul_f32 v[90:91], v[72:73], v[90:91]
	v_cvt_pk_bf16_f32 v86, v86, v87
	v_cvt_pk_bf16_f32 v87, v88, v89
	v_cvt_pk_bf16_f32 v88, v90, v91
	v_cvt_pk_bf16_f32 v89, v92, v93
	v_lshl_add_u64 v[90:91], v[82:83], 1, s[6:7]
	global_store_dwordx4 v[90:91], v[86:89], off
.LBB0_1823:
	v_readlane_b32 s24, v251, 16
	v_or_b32_e32 v82, 0x80, v82
	v_readlane_b32 s25, v251, 17
	s_and_b64 vcc, exec, s[42:43]
	s_waitcnt vmcnt(15)
	s_nop 1
	v_mov_b32_e32 v84, v208
	v_mov_b32_e32 v85, v209
	v_mov_b32_e32 v86, v210
	v_mov_b32_e32 v87, v211
	v_lshlrev_b32_e32 v88, 16, v84
	v_and_b32_e32 v89, 0xffff0000, v84
	v_lshlrev_b32_e32 v84, 16, v85
	v_and_b32_e32 v85, 0xffff0000, v85
	v_lshlrev_b32_e32 v90, 16, v86
	v_and_b32_e32 v91, 0xffff0000, v86
	v_lshlrev_b32_e32 v86, 16, v87
	v_and_b32_e32 v87, 0xffff0000, v87
	v_pk_add_f32 v[70:71], v[70:71], v[84:85]
	v_pk_add_f32 v[68:69], v[68:69], v[88:89]
	v_pk_add_f32 v[66:67], v[66:67], v[86:87]
	v_pk_add_f32 v[64:65], v[64:65], v[90:91]
	v_cvt_pk_bf16_f32 v84, v68, v69
	v_cvt_pk_bf16_f32 v85, v70, v71
	v_cvt_pk_bf16_f32 v86, v64, v65
	v_cvt_pk_bf16_f32 v87, v66, v67
	v_lshl_add_u64 v[88:89], v[82:83], 1, s[24:25]
	global_store_dwordx4 v[88:89], v[84:87], off
	s_cbranch_vccnz .LBB0_1825
	v_lshl_add_u64 v[82:83], v[82:83], 1, s[6:7]
	s_nop 3
	v_mov_b32_e32 v84, v236
	v_mov_b32_e32 v85, v237
	v_mov_b32_e32 v86, v238
	v_mov_b32_e32 v87, v239
	v_mov_b32_e32 v88, v240
	v_mov_b32_e32 v89, v241
	v_mov_b32_e32 v90, v242
	v_mov_b32_e32 v91, v243
	v_pk_mul_f32 v[86:87], v[70:71], v[86:87]
	v_pk_mul_f32 v[84:85], v[68:69], v[84:85]
	v_pk_mul_f32 v[90:91], v[66:67], v[90:91]
	v_pk_mul_f32 v[88:89], v[64:65], v[88:89]
	v_cvt_pk_bf16_f32 v84, v84, v85
	v_cvt_pk_bf16_f32 v85, v86, v87
	v_cvt_pk_bf16_f32 v86, v88, v89
	v_cvt_pk_bf16_f32 v87, v90, v91
	global_store_dwordx4 v[82:83], v[84:87], off

.LBB0_1827:
	s_or_b64 exec, exec, s[24:25]
	v_add_u32_e32 v64, 0x80, v150
	s_waitcnt lgkmcnt(0)
	v_ashrrev_i32_e32 v65, 31, v64
	v_lshlrev_b64 v[66:67], 11, v[64:65]
	v_lshl_add_u64 v[66:67], v[66:67], 0, v[148:149]
	v_readlane_b32 s52, v251, 8
	v_lshlrev_b64 v[74:75], 1, v[66:67]
	v_readlane_b32 s56, v251, 12
	v_readlane_b32 s57, v251, 13
	v_readlane_b32 s24, v251, 16
	v_readlane_b32 s25, v251, 17
	v_lshl_add_u64 v[68:69], s[56:57], 0, v[74:75]
	v_lshl_add_u64 v[74:75], s[24:25], 0, v[74:75]
	s_and_b64 vcc, exec, s[42:43]
	v_readlane_b32 s53, v251, 9
	v_readlane_b32 s54, v251, 10
	v_readlane_b32 s55, v251, 11
	v_readlane_b32 s58, v251, 14
	v_readlane_b32 s59, v251, 15
	s_waitcnt vmcnt(15)
	s_nop 1
	v_mov_b32_e32 v70, v212
	v_mov_b32_e32 v71, v213
	v_mov_b32_e32 v72, v214
	v_mov_b32_e32 v73, v215
	v_lshlrev_b32_e32 v76, 16, v70
	v_and_b32_e32 v77, 0xffff0000, v70
	v_lshlrev_b32_e32 v70, 16, v71
	v_and_b32_e32 v71, 0xffff0000, v71
	v_lshlrev_b32_e32 v78, 16, v72
	v_and_b32_e32 v79, 0xffff0000, v72
	v_lshlrev_b32_e32 v72, 16, v73
	v_and_b32_e32 v73, 0xffff0000, v73
	v_pk_add_f32 v[62:63], v[62:63], v[70:71]
	v_pk_add_f32 v[60:61], v[60:61], v[76:77]
	v_pk_add_f32 v[58:59], v[58:59], v[72:73]
	v_pk_add_f32 v[56:57], v[56:57], v[78:79]
	v_cvt_pk_bf16_f32 v70, v60, v61
	v_cvt_pk_bf16_f32 v71, v62, v63
	v_cvt_pk_bf16_f32 v72, v56, v57
	v_cvt_pk_bf16_f32 v73, v58, v59
	global_store_dwordx4 v[74:75], v[70:73], off
	s_cbranch_vccnz .LBB0_1829
	s_nop 3
	v_mov_b32_e32 v70, v228
	v_mov_b32_e32 v71, v229
	v_mov_b32_e32 v72, v230
	v_mov_b32_e32 v73, v231
	v_mov_b32_e32 v74, v232
	v_mov_b32_e32 v75, v233
	v_mov_b32_e32 v76, v234
	v_mov_b32_e32 v77, v235
	v_pk_mul_f32 v[72:73], v[62:63], v[72:73]
	v_pk_mul_f32 v[70:71], v[60:61], v[70:71]
	v_pk_mul_f32 v[76:77], v[58:59], v[76:77]
	v_pk_mul_f32 v[74:75], v[56:57], v[74:75]
	v_cvt_pk_bf16_f32 v70, v70, v71
	v_cvt_pk_bf16_f32 v71, v72, v73
	v_cvt_pk_bf16_f32 v72, v74, v75
	v_cvt_pk_bf16_f32 v73, v76, v77
	v_lshl_add_u64 v[74:75], v[66:67], 1, s[6:7]
	global_store_dwordx4 v[74:75], v[70:73], off
.LBB0_1829:
	v_readlane_b32 s24, v251, 16
	v_or_b32_e32 v66, 0x80, v66
	v_readlane_b32 s25, v251, 17
	s_and_b64 vcc, exec, s[42:43]
	s_waitcnt vmcnt(15)
	s_nop 1
	v_mov_b32_e32 v68, v216
	v_mov_b32_e32 v69, v217
	v_mov_b32_e32 v70, v218
	v_mov_b32_e32 v71, v219
	v_lshlrev_b32_e32 v72, 16, v68
	v_and_b32_e32 v73, 0xffff0000, v68
	v_lshlrev_b32_e32 v68, 16, v69
	v_and_b32_e32 v69, 0xffff0000, v69
	v_lshlrev_b32_e32 v74, 16, v70
	v_and_b32_e32 v75, 0xffff0000, v70
	v_lshlrev_b32_e32 v70, 16, v71
	v_and_b32_e32 v71, 0xffff0000, v71
	v_pk_add_f32 v[54:55], v[54:55], v[68:69]
	v_pk_add_f32 v[52:53], v[52:53], v[72:73]
	v_pk_add_f32 v[50:51], v[50:51], v[70:71]
	v_pk_add_f32 v[48:49], v[48:49], v[74:75]
	v_cvt_pk_bf16_f32 v68, v52, v53
	v_cvt_pk_bf16_f32 v69, v54, v55
	v_cvt_pk_bf16_f32 v70, v48, v49
	v_cvt_pk_bf16_f32 v71, v50, v51
	v_lshl_add_u64 v[72:73], v[66:67], 1, s[24:25]
	global_store_dwordx4 v[72:73], v[68:71], off
	s_cbranch_vccnz .LBB0_1831
	v_lshl_add_u64 v[66:67], v[66:67], 1, s[6:7]
	s_nop 3
	v_mov_b32_e32 v68, v236
	v_mov_b32_e32 v69, v237
	v_mov_b32_e32 v70, v238
	v_mov_b32_e32 v71, v239
	v_mov_b32_e32 v72, v240
	v_mov_b32_e32 v73, v241
	v_mov_b32_e32 v74, v242
	v_mov_b32_e32 v75, v243
	v_pk_mul_f32 v[70:71], v[54:55], v[70:71]
	v_pk_mul_f32 v[68:69], v[52:53], v[68:69]
	v_pk_mul_f32 v[74:75], v[50:51], v[74:75]
	v_pk_mul_f32 v[72:73], v[48:49], v[72:73]
	v_cvt_pk_bf16_f32 v68, v68, v69
	v_cvt_pk_bf16_f32 v69, v70, v71
	v_cvt_pk_bf16_f32 v70, v72, v73
	v_cvt_pk_bf16_f32 v71, v74, v75
	global_store_dwordx4 v[66:67], v[68:71], off

.LBB0_1833:
	s_or_b64 exec, exec, s[24:25]
	v_add_u32_e32 v48, 0x90, v150
	s_waitcnt lgkmcnt(0)
	v_ashrrev_i32_e32 v49, 31, v48
	v_lshlrev_b64 v[50:51], 11, v[48:49]
	v_lshl_add_u64 v[50:51], v[50:51], 0, v[148:149]
	v_readlane_b32 s52, v251, 8
	v_lshlrev_b64 v[58:59], 1, v[50:51]
	v_readlane_b32 s56, v251, 12
	v_readlane_b32 s57, v251, 13
	v_readlane_b32 s24, v251, 16
	v_readlane_b32 s25, v251, 17
	v_lshl_add_u64 v[52:53], s[56:57], 0, v[58:59]
	v_lshl_add_u64 v[58:59], s[24:25], 0, v[58:59]
	s_and_b64 vcc, exec, s[42:43]
	v_readlane_b32 s53, v251, 9
	v_readlane_b32 s54, v251, 10
	v_readlane_b32 s55, v251, 11
	v_readlane_b32 s58, v251, 14
	v_readlane_b32 s59, v251, 15
	s_waitcnt vmcnt(15)
	s_nop 1
	v_mov_b32_e32 v54, v220
	v_mov_b32_e32 v55, v221
	v_mov_b32_e32 v56, v222
	v_mov_b32_e32 v57, v223
	v_lshlrev_b32_e32 v60, 16, v54
	v_and_b32_e32 v61, 0xffff0000, v54
	v_lshlrev_b32_e32 v54, 16, v55
	v_and_b32_e32 v55, 0xffff0000, v55
	v_lshlrev_b32_e32 v62, 16, v56
	v_and_b32_e32 v63, 0xffff0000, v56
	v_lshlrev_b32_e32 v56, 16, v57
	v_and_b32_e32 v57, 0xffff0000, v57
	v_pk_add_f32 v[46:47], v[46:47], v[54:55]
	v_pk_add_f32 v[44:45], v[44:45], v[60:61]
	v_pk_add_f32 v[42:43], v[42:43], v[56:57]
	v_pk_add_f32 v[40:41], v[40:41], v[62:63]
	v_cvt_pk_bf16_f32 v54, v44, v45
	v_cvt_pk_bf16_f32 v55, v46, v47
	v_cvt_pk_bf16_f32 v56, v40, v41
	v_cvt_pk_bf16_f32 v57, v42, v43
	global_store_dwordx4 v[58:59], v[54:57], off
	s_cbranch_vccnz .LBB0_1835
	s_nop 3
	v_mov_b32_e32 v54, v228
	v_mov_b32_e32 v55, v229
	v_mov_b32_e32 v56, v230
	v_mov_b32_e32 v57, v231
	v_mov_b32_e32 v58, v232
	v_mov_b32_e32 v59, v233
	v_mov_b32_e32 v60, v234
	v_mov_b32_e32 v61, v235
	v_pk_mul_f32 v[56:57], v[46:47], v[56:57]
	v_pk_mul_f32 v[54:55], v[44:45], v[54:55]
	v_pk_mul_f32 v[60:61], v[42:43], v[60:61]
	v_pk_mul_f32 v[58:59], v[40:41], v[58:59]
	v_cvt_pk_bf16_f32 v54, v54, v55
	v_cvt_pk_bf16_f32 v55, v56, v57
	v_cvt_pk_bf16_f32 v56, v58, v59
	v_cvt_pk_bf16_f32 v57, v60, v61
	v_lshl_add_u64 v[58:59], v[50:51], 1, s[6:7]
	global_store_dwordx4 v[58:59], v[54:57], off
.LBB0_1835:
	v_readlane_b32 s24, v251, 16
	v_or_b32_e32 v50, 0x80, v50
	v_readlane_b32 s25, v251, 17
	s_and_b64 vcc, exec, s[42:43]
	s_waitcnt vmcnt(15)
	s_nop 1
	v_mov_b32_e32 v52, v224
	v_mov_b32_e32 v53, v225
	v_mov_b32_e32 v54, v226
	v_mov_b32_e32 v55, v227
	v_lshlrev_b32_e32 v56, 16, v52
	v_and_b32_e32 v57, 0xffff0000, v52
	v_lshlrev_b32_e32 v52, 16, v53
	v_and_b32_e32 v53, 0xffff0000, v53
	v_lshlrev_b32_e32 v58, 16, v54
	v_and_b32_e32 v59, 0xffff0000, v54
	v_lshlrev_b32_e32 v54, 16, v55
	v_and_b32_e32 v55, 0xffff0000, v55
	v_pk_add_f32 v[38:39], v[38:39], v[52:53]
	v_pk_add_f32 v[36:37], v[36:37], v[56:57]
	v_pk_add_f32 v[34:35], v[34:35], v[54:55]
	v_pk_add_f32 v[32:33], v[32:33], v[58:59]
	v_cvt_pk_bf16_f32 v52, v36, v37
	v_cvt_pk_bf16_f32 v53, v38, v39
	v_cvt_pk_bf16_f32 v54, v32, v33
	v_cvt_pk_bf16_f32 v55, v34, v35
	v_lshl_add_u64 v[56:57], v[50:51], 1, s[24:25]
	global_store_dwordx4 v[56:57], v[52:55], off
	s_cbranch_vccnz .LBB0_1837
	v_lshl_add_u64 v[50:51], v[50:51], 1, s[6:7]
	s_nop 3
	v_mov_b32_e32 v52, v236
	v_mov_b32_e32 v53, v237
	v_mov_b32_e32 v54, v238
	v_mov_b32_e32 v55, v239
	v_mov_b32_e32 v56, v240
	v_mov_b32_e32 v57, v241
	v_mov_b32_e32 v58, v242
	v_mov_b32_e32 v59, v243
	v_pk_mul_f32 v[54:55], v[38:39], v[54:55]
	v_pk_mul_f32 v[52:53], v[36:37], v[52:53]
	v_pk_mul_f32 v[58:59], v[34:35], v[58:59]
	v_pk_mul_f32 v[56:57], v[32:33], v[56:57]
	v_cvt_pk_bf16_f32 v52, v52, v53
	v_cvt_pk_bf16_f32 v53, v54, v55
	v_cvt_pk_bf16_f32 v54, v56, v57
	v_cvt_pk_bf16_f32 v55, v58, v59
	global_store_dwordx4 v[50:51], v[52:55], off

.LBB0_1839:
	s_or_b64 exec, exec, s[24:25]
	v_add_u32_e32 v32, 0xa0, v150
	s_waitcnt lgkmcnt(0)
	v_ashrrev_i32_e32 v33, 31, v32
	v_lshlrev_b64 v[34:35], 11, v[32:33]
	v_lshl_add_u64 v[34:35], v[34:35], 0, v[148:149]
	v_readlane_b32 s52, v251, 8
	v_lshlrev_b64 v[42:43], 1, v[34:35]
	v_readlane_b32 s56, v251, 12
	v_readlane_b32 s57, v251, 13
	v_readlane_b32 s24, v251, 16
	v_readlane_b32 s25, v251, 17
	v_lshl_add_u64 v[36:37], s[56:57], 0, v[42:43]
	v_lshl_add_u64 v[42:43], s[24:25], 0, v[42:43]
	s_and_b64 vcc, exec, s[42:43]
	v_readlane_b32 s53, v251, 9
	v_readlane_b32 s54, v251, 10
	v_readlane_b32 s55, v251, 11
	v_readlane_b32 s58, v251, 14
	v_readlane_b32 s59, v251, 15
	s_waitcnt vmcnt(15)
	s_nop 1
	v_mov_b32_e32 v38, v178
	v_mov_b32_e32 v39, v179
	v_mov_b32_e32 v40, v180
	v_mov_b32_e32 v41, v181
	v_lshlrev_b32_e32 v44, 16, v38
	v_and_b32_e32 v45, 0xffff0000, v38
	v_lshlrev_b32_e32 v38, 16, v39
	v_and_b32_e32 v39, 0xffff0000, v39
	v_lshlrev_b32_e32 v46, 16, v40
	v_and_b32_e32 v47, 0xffff0000, v40
	v_lshlrev_b32_e32 v40, 16, v41
	v_and_b32_e32 v41, 0xffff0000, v41
	v_pk_add_f32 v[30:31], v[30:31], v[38:39]
	v_pk_add_f32 v[28:29], v[28:29], v[44:45]
	v_pk_add_f32 v[26:27], v[26:27], v[40:41]
	v_pk_add_f32 v[24:25], v[24:25], v[46:47]
	v_cvt_pk_bf16_f32 v38, v28, v29
	v_cvt_pk_bf16_f32 v39, v30, v31
	v_cvt_pk_bf16_f32 v40, v24, v25
	v_cvt_pk_bf16_f32 v41, v26, v27
	global_store_dwordx4 v[42:43], v[38:41], off
	s_cbranch_vccnz .LBB0_1841
	s_nop 3
	v_mov_b32_e32 v38, v228
	v_mov_b32_e32 v39, v229
	v_mov_b32_e32 v40, v230
	v_mov_b32_e32 v41, v231
	v_mov_b32_e32 v42, v232
	v_mov_b32_e32 v43, v233
	v_mov_b32_e32 v44, v234
	v_mov_b32_e32 v45, v235
	v_pk_mul_f32 v[40:41], v[30:31], v[40:41]
	v_pk_mul_f32 v[38:39], v[28:29], v[38:39]
	v_pk_mul_f32 v[44:45], v[26:27], v[44:45]
	v_pk_mul_f32 v[42:43], v[24:25], v[42:43]
	v_cvt_pk_bf16_f32 v38, v38, v39
	v_cvt_pk_bf16_f32 v39, v40, v41
	v_cvt_pk_bf16_f32 v40, v42, v43
	v_cvt_pk_bf16_f32 v41, v44, v45
	v_lshl_add_u64 v[42:43], v[34:35], 1, s[6:7]
	global_store_dwordx4 v[42:43], v[38:41], off
.LBB0_1841:
	v_readlane_b32 s24, v251, 16
	v_or_b32_e32 v34, 0x80, v34
	v_readlane_b32 s25, v251, 17
	s_and_b64 vcc, exec, s[42:43]
	s_waitcnt vmcnt(14)
	s_nop 1
	v_mov_b32_e32 v36, v182
	v_mov_b32_e32 v37, v183
	v_mov_b32_e32 v38, v184
	v_mov_b32_e32 v39, v185
	v_lshlrev_b32_e32 v40, 16, v36
	v_and_b32_e32 v41, 0xffff0000, v36
	v_lshlrev_b32_e32 v36, 16, v37
	v_and_b32_e32 v37, 0xffff0000, v37
	v_lshlrev_b32_e32 v42, 16, v38
	v_and_b32_e32 v43, 0xffff0000, v38
	v_lshlrev_b32_e32 v38, 16, v39
	v_and_b32_e32 v39, 0xffff0000, v39
	v_pk_add_f32 v[22:23], v[22:23], v[36:37]
	v_pk_add_f32 v[20:21], v[20:21], v[40:41]
	v_pk_add_f32 v[18:19], v[18:19], v[38:39]
	v_pk_add_f32 v[16:17], v[16:17], v[42:43]
	v_cvt_pk_bf16_f32 v36, v20, v21
	v_cvt_pk_bf16_f32 v37, v22, v23
	v_cvt_pk_bf16_f32 v38, v16, v17
	v_cvt_pk_bf16_f32 v39, v18, v19
	v_lshl_add_u64 v[40:41], v[34:35], 1, s[24:25]
	global_store_dwordx4 v[40:41], v[36:39], off
	s_cbranch_vccnz .LBB0_1843
	v_lshl_add_u64 v[34:35], v[34:35], 1, s[6:7]
	s_nop 3
	v_mov_b32_e32 v36, v236
	v_mov_b32_e32 v37, v237
	v_mov_b32_e32 v38, v238
	v_mov_b32_e32 v39, v239
	v_mov_b32_e32 v40, v240
	v_mov_b32_e32 v41, v241
	v_mov_b32_e32 v42, v242
	v_mov_b32_e32 v43, v243
	v_pk_mul_f32 v[38:39], v[22:23], v[38:39]
	v_pk_mul_f32 v[36:37], v[20:21], v[36:37]
	v_pk_mul_f32 v[42:43], v[18:19], v[42:43]
	v_pk_mul_f32 v[40:41], v[16:17], v[40:41]
	v_cvt_pk_bf16_f32 v36, v36, v37
	v_cvt_pk_bf16_f32 v37, v38, v39
	v_cvt_pk_bf16_f32 v38, v40, v41
	v_cvt_pk_bf16_f32 v39, v42, v43
	global_store_dwordx4 v[34:35], v[36:39], off

.LBB0_1845:
	s_or_b64 exec, exec, s[24:25]
	v_add_u32_e32 v16, 0xb0, v150
	s_waitcnt lgkmcnt(0)
	v_ashrrev_i32_e32 v17, 31, v16
	v_lshlrev_b64 v[18:19], 11, v[16:17]
	v_lshl_add_u64 v[18:19], v[18:19], 0, v[148:149]
	v_readlane_b32 s52, v251, 8
	v_lshlrev_b64 v[26:27], 1, v[18:19]
	v_readlane_b32 s56, v251, 12
	v_readlane_b32 s57, v251, 13
	v_readlane_b32 s24, v251, 16
	v_readlane_b32 s25, v251, 17
	v_lshl_add_u64 v[20:21], s[56:57], 0, v[26:27]
	v_lshl_add_u64 v[26:27], s[24:25], 0, v[26:27]
	s_and_b64 vcc, exec, s[42:43]
	v_readlane_b32 s53, v251, 9
	v_readlane_b32 s54, v251, 10
	v_readlane_b32 s55, v251, 11
	v_readlane_b32 s58, v251, 14
	v_readlane_b32 s59, v251, 15
	s_waitcnt vmcnt(13)
	s_nop 1
	v_mov_b32_e32 v22, v186
	v_mov_b32_e32 v23, v187
	v_mov_b32_e32 v24, v188
	v_mov_b32_e32 v25, v189
	v_lshlrev_b32_e32 v28, 16, v22
	v_and_b32_e32 v29, 0xffff0000, v22
	v_lshlrev_b32_e32 v22, 16, v23
	v_and_b32_e32 v23, 0xffff0000, v23
	v_lshlrev_b32_e32 v30, 16, v24
	v_and_b32_e32 v31, 0xffff0000, v24
	v_lshlrev_b32_e32 v24, 16, v25
	v_and_b32_e32 v25, 0xffff0000, v25
	v_pk_add_f32 v[14:15], v[14:15], v[22:23]
	v_pk_add_f32 v[12:13], v[12:13], v[28:29]
	v_pk_add_f32 v[10:11], v[10:11], v[24:25]
	v_pk_add_f32 v[8:9], v[8:9], v[30:31]
	v_cvt_pk_bf16_f32 v22, v12, v13
	v_cvt_pk_bf16_f32 v23, v14, v15
	v_cvt_pk_bf16_f32 v24, v8, v9
	v_cvt_pk_bf16_f32 v25, v10, v11
	global_store_dwordx4 v[26:27], v[22:25], off
	s_cbranch_vccnz .LBB0_1847
	s_nop 3
	v_mov_b32_e32 v22, v228
	v_mov_b32_e32 v23, v229
	v_mov_b32_e32 v24, v230
	v_mov_b32_e32 v25, v231
	v_mov_b32_e32 v26, v232
	v_mov_b32_e32 v27, v233
	v_mov_b32_e32 v28, v234
	v_mov_b32_e32 v29, v235
	v_pk_mul_f32 v[24:25], v[14:15], v[24:25]
	v_pk_mul_f32 v[22:23], v[12:13], v[22:23]
	v_pk_mul_f32 v[28:29], v[10:11], v[28:29]
	v_pk_mul_f32 v[26:27], v[8:9], v[26:27]
	v_cvt_pk_bf16_f32 v22, v22, v23
	v_cvt_pk_bf16_f32 v23, v24, v25
	v_cvt_pk_bf16_f32 v24, v26, v27
	v_cvt_pk_bf16_f32 v25, v28, v29
	v_lshl_add_u64 v[26:27], v[18:19], 1, s[6:7]
	global_store_dwordx4 v[26:27], v[22:25], off
.LBB0_1847:
	v_readlane_b32 s24, v251, 16
	v_or_b32_e32 v18, 0x80, v18
	v_readlane_b32 s25, v251, 17
	s_and_b64 vcc, exec, s[42:43]
	s_waitcnt vmcnt(12)
	s_nop 1
	v_mov_b32_e32 v20, v192
	v_mov_b32_e32 v21, v193
	v_mov_b32_e32 v22, v194
	v_mov_b32_e32 v23, v195
	v_lshlrev_b32_e32 v24, 16, v20
	v_and_b32_e32 v25, 0xffff0000, v20
	v_lshlrev_b32_e32 v20, 16, v21
	v_and_b32_e32 v21, 0xffff0000, v21
	v_lshlrev_b32_e32 v26, 16, v22
	v_and_b32_e32 v27, 0xffff0000, v22
	v_lshlrev_b32_e32 v22, 16, v23
	v_and_b32_e32 v23, 0xffff0000, v23
	v_pk_add_f32 v[6:7], v[6:7], v[20:21]
	v_pk_add_f32 v[4:5], v[4:5], v[24:25]
	v_pk_add_f32 v[2:3], v[2:3], v[22:23]
	v_pk_add_f32 v[0:1], v[0:1], v[26:27]
	v_cvt_pk_bf16_f32 v20, v4, v5
	v_cvt_pk_bf16_f32 v21, v6, v7
	v_cvt_pk_bf16_f32 v22, v0, v1
	v_cvt_pk_bf16_f32 v23, v2, v3
	v_lshl_add_u64 v[24:25], v[18:19], 1, s[24:25]
	global_store_dwordx4 v[24:25], v[20:23], off
	s_cbranch_vccnz .LBB0_1849
	v_lshl_add_u64 v[18:19], v[18:19], 1, s[6:7]
	s_nop 3
	v_mov_b32_e32 v20, v236
	v_mov_b32_e32 v21, v237
	v_mov_b32_e32 v22, v238
	v_mov_b32_e32 v23, v239
	v_mov_b32_e32 v24, v240
	v_mov_b32_e32 v25, v241
	v_mov_b32_e32 v26, v242
	v_mov_b32_e32 v27, v243
	v_pk_mul_f32 v[22:23], v[6:7], v[22:23]
	v_pk_mul_f32 v[20:21], v[4:5], v[20:21]
	v_pk_mul_f32 v[26:27], v[2:3], v[26:27]
	v_pk_mul_f32 v[24:25], v[0:1], v[24:25]
	v_cvt_pk_bf16_f32 v20, v20, v21
	v_cvt_pk_bf16_f32 v21, v22, v23
	v_cvt_pk_bf16_f32 v22, v24, v25
	v_cvt_pk_bf16_f32 v23, v26, v27
	global_store_dwordx4 v[18:19], v[20:23], off

.LBB0_2047:
	v_lshl_add_u32 v18, s42, 8, v160
	v_lshl_or_b32 v16, s41, 8, v162
	v_ashrrev_i32_e32 v19, 31, v18
	v_ashrrev_i32_e32 v17, 31, v16
	v_lshlrev_b64 v[24:25], 11, v[18:19]
	v_lshl_add_u64 v[40:41], v[24:25], 0, v[16:17]
	v_readlane_b32 s42, v251, 16
	v_lshlrev_b64 v[42:43], 1, v[40:41]
	v_readlane_b32 s43, v251, 17
	v_readlane_b32 s24, v251, 8
	v_readlane_b32 s28, v251, 12
	v_lshl_add_u64 v[24:25], s[42:43], 0, v[42:43]
	v_mov_b32_e32 v244, v24
	v_mov_b32_e32 v245, v25
	global_load_dwordx4 v[178:181], v[244:245], off
	global_load_dwordx4 v[182:185], v[244:245], off offset:256
	s_mov_b64 s[30:31], 0x10000
	v_lshl_add_u64 v[244:245], v[244:245], 0, s[30:31]
	global_load_dwordx4 v[186:189], v[244:245], off
	global_load_dwordx4 v[192:195], v[244:245], off offset:256
	v_lshl_add_u64 v[244:245], v[244:245], 0, s[30:31]
	global_load_dwordx4 v[196:199], v[244:245], off
	global_load_dwordx4 v[200:203], v[244:245], off offset:256
	v_lshl_add_u64 v[244:245], v[244:245], 0, s[30:31]
	global_load_dwordx4 v[204:207], v[244:245], off
	global_load_dwordx4 v[208:211], v[244:245], off offset:256
	s_mov_b64 s[30:31], 0x50000
	v_lshl_add_u64 v[244:245], v[244:245], 0, s[30:31]
	global_load_dwordx4 v[212:215], v[244:245], off
	global_load_dwordx4 v[216:219], v[244:245], off offset:256
	s_mov_b64 s[30:31], 0x10000
	v_lshl_add_u64 v[244:245], v[244:245], 0, s[30:31]
	global_load_dwordx4 v[220:223], v[244:245], off
	global_load_dwordx4 v[224:227], v[244:245], off offset:256
	v_lshl_add_u64 v[244:245], v[244:245], 0, s[30:31]
	global_load_dwordx4 v[228:231], v[244:245], off
	global_load_dwordx4 v[232:235], v[244:245], off offset:256
	v_lshl_add_u64 v[244:245], v[244:245], 0, s[30:31]
	global_load_dwordx4 v[236:239], v[244:245], off
	global_load_dwordx4 v[240:243], v[244:245], off offset:256
	v_readlane_b32 s29, v251, 13
	v_or_b32_e32 v42, 0x100, v42
	v_lshl_add_u64 v[176:177], s[42:43], 0, v[42:43]
	v_lshl_add_u64 v[174:175], v[40:41], 2, s[28:29]
	v_readlane_b32 s25, v251, 9
	v_readlane_b32 s26, v251, 10
	v_readlane_b32 s27, v251, 11
	v_readlane_b32 s30, v251, 14
	v_readlane_b32 s31, v251, 15
	s_waitcnt vmcnt(15)
	s_nop 1
	v_mov_b32_e32 v24, v178
	v_mov_b32_e32 v25, v179
	v_mov_b32_e32 v26, v180
	v_mov_b32_e32 v27, v181
	v_lshlrev_b32_e32 v40, 16, v24
	v_and_b32_e32 v41, 0xffff0000, v24
	v_lshlrev_b32_e32 v24, 16, v25
	v_and_b32_e32 v25, 0xffff0000, v25
	v_lshlrev_b32_e32 v166, 16, v26
	v_and_b32_e32 v167, 0xffff0000, v26
	v_lshlrev_b32_e32 v26, 16, v27
	v_and_b32_e32 v27, 0xffff0000, v27
	v_pk_add_f32 v[42:43], v[126:127], v[24:25]
	v_pk_add_f32 v[40:41], v[148:149], v[40:41]
	v_pk_add_f32 v[168:169], v[156:157], v[26:27]
	v_pk_add_f32 v[166:167], v[158:159], v[166:167]
	global_store_dwordx4 v[174:175], v[40:43], off
	global_store_dwordx4 v[174:175], v[166:169], off offset:16
	v_add_u32_e32 v27, 64, v171
	v_cmp_lt_i32_e32 vcc, v172, v27
	v_mul_f32_e32 v25, v43, v43
	v_fmac_f32_e32 v25, v42, v42
	v_cndmask_b32_e32 v24, v191, v172, vcc
	v_lshlrev_b32_e32 v26, 2, v24
	v_mul_f32_e32 v24, v41, v41
	v_mul_f32_e32 v41, v167, v167
	v_fmac_f32_e32 v24, v40, v40
	v_mul_f32_e32 v43, v169, v169
	v_fmac_f32_e32 v41, v166, v166
	v_add_f32_e32 v24, v24, v25
	v_fmac_f32_e32 v43, v168, v168
	v_add_f32_e32 v24, v41, v24
	v_add_f32_e32 v166, v43, v24
	v_cmp_lt_i32_e32 vcc, v173, v27
	s_waitcnt vmcnt(16)
	s_nop 1
	v_mov_b32_e32 v156, v182
	v_mov_b32_e32 v157, v183
	v_mov_b32_e32 v158, v184
	v_mov_b32_e32 v159, v185
	v_lshlrev_b32_e32 v24, 16, v156
	v_and_b32_e32 v25, 0xffff0000, v156
	v_lshlrev_b32_e32 v40, 16, v157
	v_and_b32_e32 v41, 0xffff0000, v157
	v_lshlrev_b32_e32 v148, 16, v158
	v_and_b32_e32 v149, 0xffff0000, v158
	v_pk_add_f32 v[42:43], v[154:155], v[40:41]
	v_pk_add_f32 v[40:41], v[152:153], v[24:25]
	v_lshlrev_b32_e32 v126, 16, v159
	v_and_b32_e32 v127, 0xffff0000, v159
	v_pk_add_f32 v[124:125], v[124:125], v[148:149]
	v_mul_f32_e32 v24, v41, v41
	v_mul_f32_e32 v25, v43, v43
	v_pk_add_f32 v[126:127], v[150:151], v[126:127]
	v_mul_f32_e32 v148, v125, v125
	v_fmac_f32_e32 v24, v40, v40
	v_fmac_f32_e32 v25, v42, v42
	v_mul_f32_e32 v149, v127, v127
	v_fmac_f32_e32 v148, v124, v124
	v_add_f32_e32 v24, v24, v25
	v_add_f32_e32 v24, v148, v24
	v_fmac_f32_e32 v149, v126, v126
	v_add_f32_e32 v24, v149, v24
	v_add_f32_e32 v24, v166, v24
	ds_bpermute_b32 v25, v26, v24
	v_cndmask_b32_e32 v27, v191, v173, vcc
	v_lshlrev_b32_e32 v27, 2, v27
	global_store_dwordx4 v[174:175], v[40:43], off offset:512
	global_store_dwordx4 v[174:175], v[124:127], off offset:528
	s_waitcnt lgkmcnt(0)
	v_add_f32_e32 v24, v24, v25
	ds_bpermute_b32 v25, v27, v24
	s_and_saveexec_b64 s[24:25], s[0:1]
	s_cbranch_execz .LBB0_2049
	v_lshl_add_u64 v[40:41], v[18:19], 2, s[6:7]
	s_waitcnt lgkmcnt(0)
	v_add_f32_e32 v19, v24, v25
	global_atomic_add_f32 v[40:41], v19, off
.LBB0_2049:
	s_or_b64 exec, exec, s[24:25]
	v_or_b32_e32 v24, 16, v18
	s_waitcnt lgkmcnt(0)
	v_ashrrev_i32_e32 v25, 31, v24
	v_lshlrev_b64 v[40:41], 11, v[24:25]
	v_lshl_add_u64 v[124:125], v[40:41], 0, v[16:17]
	v_readlane_b32 s42, v251, 16
	v_lshlrev_b64 v[126:127], 1, v[124:125]
	v_readlane_b32 s43, v251, 17
	v_readlane_b32 s24, v251, 8
	v_readlane_b32 s28, v251, 12
	v_lshl_add_u64 v[40:41], s[42:43], 0, v[126:127]
	v_readlane_b32 s29, v251, 13
	v_or_b32_e32 v126, 0x100, v126
	v_readlane_b32 s25, v251, 9
	v_lshl_add_u64 v[148:149], v[124:125], 2, s[28:29]
	v_lshl_add_u64 v[124:125], s[42:43], 0, v[126:127]
	v_readlane_b32 s26, v251, 10
	v_readlane_b32 s27, v251, 11
	v_readlane_b32 s30, v251, 14
	v_readlane_b32 s31, v251, 15
	s_waitcnt vmcnt(17)
	s_nop 1
	v_mov_b32_e32 v40, v186
	v_mov_b32_e32 v41, v187
	v_mov_b32_e32 v42, v188
	v_mov_b32_e32 v43, v189
	v_lshlrev_b32_e32 v126, 16, v40
	v_and_b32_e32 v127, 0xffff0000, v40
	v_lshlrev_b32_e32 v40, 16, v41
	v_and_b32_e32 v41, 0xffff0000, v41
	v_lshlrev_b32_e32 v150, 16, v42
	v_and_b32_e32 v151, 0xffff0000, v42
	v_lshlrev_b32_e32 v152, 16, v43
	v_and_b32_e32 v153, 0xffff0000, v43
	v_pk_add_f32 v[42:43], v[108:109], v[40:41]
	v_pk_add_f32 v[40:41], v[110:111], v[126:127]
	v_pk_add_f32 v[110:111], v[114:115], v[152:153]
	v_pk_add_f32 v[108:109], v[120:121], v[150:151]
	global_store_dwordx4 v[148:149], v[40:43], off
	global_store_dwordx4 v[148:149], v[108:111], off offset:16
	v_mul_f32_e32 v19, v41, v41
	v_mul_f32_e32 v41, v43, v43
	v_mul_f32_e32 v43, v109, v109
	v_fmac_f32_e32 v19, v40, v40
	v_fmac_f32_e32 v41, v42, v42
	v_mul_f32_e32 v109, v111, v111
	v_fmac_f32_e32 v43, v108, v108
	v_add_f32_e32 v19, v19, v41
	v_fmac_f32_e32 v109, v110, v110
	v_add_f32_e32 v19, v43, v19
	v_add_f32_e32 v19, v109, v19
	s_waitcnt vmcnt(18)
	s_nop 1
	v_mov_b32_e32 v124, v192
	v_mov_b32_e32 v125, v193
	v_mov_b32_e32 v126, v194
	v_mov_b32_e32 v127, v195
	v_lshlrev_b32_e32 v40, 16, v124
	v_and_b32_e32 v41, 0xffff0000, v124
	v_lshlrev_b32_e32 v42, 16, v125
	v_and_b32_e32 v43, 0xffff0000, v125
	v_lshlrev_b32_e32 v120, 16, v126
	v_and_b32_e32 v121, 0xffff0000, v126
	v_pk_add_f32 v[110:111], v[122:123], v[42:43]
	v_pk_add_f32 v[108:109], v[118:119], v[40:41]
	v_lshlrev_b32_e32 v114, 16, v127
	v_and_b32_e32 v115, 0xffff0000, v127
	v_pk_add_f32 v[112:113], v[112:113], v[120:121]
	v_mul_f32_e32 v40, v109, v109
	v_mul_f32_e32 v41, v111, v111
	v_pk_add_f32 v[114:115], v[116:117], v[114:115]
	v_mul_f32_e32 v42, v113, v113
	v_fmac_f32_e32 v40, v108, v108
	v_fmac_f32_e32 v41, v110, v110
	v_mul_f32_e32 v43, v115, v115
	v_fmac_f32_e32 v42, v112, v112
	v_add_f32_e32 v40, v40, v41
	v_add_f32_e32 v40, v42, v40
	v_fmac_f32_e32 v43, v114, v114
	v_add_f32_e32 v40, v43, v40
	v_add_f32_e32 v19, v19, v40
	ds_bpermute_b32 v40, v26, v19
	global_store_dwordx4 v[148:149], v[108:111], off offset:512
	global_store_dwordx4 v[148:149], v[112:115], off offset:528
	s_waitcnt lgkmcnt(0)
	v_add_f32_e32 v19, v19, v40
	ds_bpermute_b32 v40, v27, v19
	s_and_saveexec_b64 s[24:25], s[0:1]
	s_cbranch_execz .LBB0_2051
	v_lshl_add_u64 v[24:25], v[24:25], 2, s[6:7]
	s_waitcnt lgkmcnt(0)
	v_add_f32_e32 v19, v19, v40
	global_atomic_add_f32 v[24:25], v19, off
.LBB0_2051:
	s_or_b64 exec, exec, s[24:25]
	v_or_b32_e32 v24, 32, v18
	v_ashrrev_i32_e32 v25, 31, v24
	s_waitcnt lgkmcnt(0)
	v_lshlrev_b64 v[40:41], 11, v[24:25]
	v_lshl_add_u64 v[108:109], v[40:41], 0, v[16:17]
	v_readlane_b32 s42, v251, 16
	v_lshlrev_b64 v[110:111], 1, v[108:109]
	v_readlane_b32 s43, v251, 17
	v_readlane_b32 s24, v251, 8
	v_readlane_b32 s28, v251, 12
	v_lshl_add_u64 v[40:41], s[42:43], 0, v[110:111]
	v_readlane_b32 s29, v251, 13
	v_or_b32_e32 v110, 0x100, v110
	v_readlane_b32 s25, v251, 9
	v_lshl_add_u64 v[112:113], v[108:109], 2, s[28:29]
	v_lshl_add_u64 v[108:109], s[42:43], 0, v[110:111]
	v_readlane_b32 s26, v251, 10
	v_readlane_b32 s27, v251, 11
	v_readlane_b32 s30, v251, 14
	v_readlane_b32 s31, v251, 15
	s_waitcnt vmcnt(19)
	s_nop 1
	v_mov_b32_e32 v40, v196
	v_mov_b32_e32 v41, v197
	v_mov_b32_e32 v42, v198
	v_mov_b32_e32 v43, v199
	v_lshlrev_b32_e32 v110, 16, v40
	v_and_b32_e32 v111, 0xffff0000, v40
	v_lshlrev_b32_e32 v40, 16, v41
	v_and_b32_e32 v41, 0xffff0000, v41
	v_lshlrev_b32_e32 v114, 16, v42
	v_and_b32_e32 v115, 0xffff0000, v42
	v_lshlrev_b32_e32 v116, 16, v43
	v_and_b32_e32 v117, 0xffff0000, v43
	v_pk_add_f32 v[42:43], v[92:93], v[40:41]
	v_pk_add_f32 v[40:41], v[94:95], v[110:111]
	v_pk_add_f32 v[94:95], v[98:99], v[116:117]
	v_pk_add_f32 v[92:93], v[104:105], v[114:115]
	global_store_dwordx4 v[112:113], v[40:43], off
	global_store_dwordx4 v[112:113], v[92:95], off offset:16
	v_mul_f32_e32 v19, v41, v41
	v_mul_f32_e32 v41, v43, v43
	v_mul_f32_e32 v43, v93, v93
	v_fmac_f32_e32 v19, v40, v40
	v_fmac_f32_e32 v41, v42, v42
	v_mul_f32_e32 v93, v95, v95
	v_fmac_f32_e32 v43, v92, v92
	v_add_f32_e32 v19, v19, v41
	v_fmac_f32_e32 v93, v94, v94
	v_add_f32_e32 v19, v43, v19
	v_add_f32_e32 v19, v93, v19
	s_waitcnt vmcnt(20)
	s_nop 1
	v_mov_b32_e32 v108, v200
	v_mov_b32_e32 v109, v201
	v_mov_b32_e32 v110, v202
	v_mov_b32_e32 v111, v203
	v_lshlrev_b32_e32 v40, 16, v108
	v_and_b32_e32 v41, 0xffff0000, v108
	v_lshlrev_b32_e32 v42, 16, v109
	v_and_b32_e32 v43, 0xffff0000, v109
	v_lshlrev_b32_e32 v104, 16, v110
	v_and_b32_e32 v105, 0xffff0000, v110
	v_pk_add_f32 v[94:95], v[106:107], v[42:43]
	v_pk_add_f32 v[92:93], v[102:103], v[40:41]
	v_lshlrev_b32_e32 v98, 16, v111
	v_and_b32_e32 v99, 0xffff0000, v111
	v_pk_add_f32 v[96:97], v[96:97], v[104:105]
	v_mul_f32_e32 v40, v93, v93
	v_mul_f32_e32 v41, v95, v95
	v_pk_add_f32 v[98:99], v[100:101], v[98:99]
	v_mul_f32_e32 v42, v97, v97
	v_fmac_f32_e32 v40, v92, v92
	v_fmac_f32_e32 v41, v94, v94
	v_mul_f32_e32 v43, v99, v99
	v_fmac_f32_e32 v42, v96, v96
	v_add_f32_e32 v40, v40, v41
	v_add_f32_e32 v40, v42, v40
	v_fmac_f32_e32 v43, v98, v98
	v_add_f32_e32 v40, v43, v40
	v_add_f32_e32 v19, v19, v40
	ds_bpermute_b32 v40, v26, v19
	global_store_dwordx4 v[112:113], v[92:95], off offset:512
	global_store_dwordx4 v[112:113], v[96:99], off offset:528
	s_waitcnt lgkmcnt(0)
	v_add_f32_e32 v19, v19, v40
	ds_bpermute_b32 v40, v27, v19
	s_and_saveexec_b64 s[24:25], s[0:1]
	s_cbranch_execz .LBB0_2053
	v_lshl_add_u64 v[24:25], v[24:25], 2, s[6:7]
	s_waitcnt lgkmcnt(0)
	v_add_f32_e32 v19, v19, v40
	global_atomic_add_f32 v[24:25], v19, off
.LBB0_2053:
	s_or_b64 exec, exec, s[24:25]
	v_or_b32_e32 v24, 48, v18
	v_ashrrev_i32_e32 v25, 31, v24
	s_waitcnt lgkmcnt(0)
	v_lshlrev_b64 v[40:41], 11, v[24:25]
	v_lshl_add_u64 v[92:93], v[40:41], 0, v[16:17]
	v_readlane_b32 s42, v251, 16
	v_lshlrev_b64 v[94:95], 1, v[92:93]
	v_readlane_b32 s43, v251, 17
	v_readlane_b32 s24, v251, 8
	v_readlane_b32 s28, v251, 12
	v_lshl_add_u64 v[40:41], s[42:43], 0, v[94:95]
	v_readlane_b32 s29, v251, 13
	v_or_b32_e32 v94, 0x100, v94
	v_readlane_b32 s25, v251, 9
	v_lshl_add_u64 v[96:97], v[92:93], 2, s[28:29]
	v_lshl_add_u64 v[92:93], s[42:43], 0, v[94:95]
	v_readlane_b32 s26, v251, 10
	v_readlane_b32 s27, v251, 11
	v_readlane_b32 s30, v251, 14
	v_readlane_b32 s31, v251, 15
	s_waitcnt vmcnt(21)
	s_nop 1
	v_mov_b32_e32 v40, v204
	v_mov_b32_e32 v41, v205
	v_mov_b32_e32 v42, v206
	v_mov_b32_e32 v43, v207
	v_lshlrev_b32_e32 v94, 16, v40
	v_and_b32_e32 v95, 0xffff0000, v40
	v_lshlrev_b32_e32 v40, 16, v41
	v_and_b32_e32 v41, 0xffff0000, v41
	v_lshlrev_b32_e32 v98, 16, v42
	v_and_b32_e32 v99, 0xffff0000, v42
	v_lshlrev_b32_e32 v100, 16, v43
	v_and_b32_e32 v101, 0xffff0000, v43
	v_pk_add_f32 v[42:43], v[76:77], v[40:41]
	v_pk_add_f32 v[40:41], v[78:79], v[94:95]
	v_pk_add_f32 v[78:79], v[82:83], v[100:101]
	v_pk_add_f32 v[76:77], v[88:89], v[98:99]
	global_store_dwordx4 v[96:97], v[40:43], off
	global_store_dwordx4 v[96:97], v[76:79], off offset:16
	v_mul_f32_e32 v19, v41, v41
	v_mul_f32_e32 v41, v43, v43
	v_mul_f32_e32 v43, v77, v77
	v_fmac_f32_e32 v19, v40, v40
	v_fmac_f32_e32 v41, v42, v42
	v_mul_f32_e32 v77, v79, v79
	v_fmac_f32_e32 v43, v76, v76
	v_add_f32_e32 v19, v19, v41
	v_fmac_f32_e32 v77, v78, v78
	v_add_f32_e32 v19, v43, v19
	v_add_f32_e32 v19, v77, v19
	s_waitcnt vmcnt(22)
	s_nop 1
	v_mov_b32_e32 v92, v208
	v_mov_b32_e32 v93, v209
	v_mov_b32_e32 v94, v210
	v_mov_b32_e32 v95, v211
	v_lshlrev_b32_e32 v40, 16, v92
	v_and_b32_e32 v41, 0xffff0000, v92
	v_lshlrev_b32_e32 v42, 16, v93
	v_and_b32_e32 v43, 0xffff0000, v93
	v_lshlrev_b32_e32 v88, 16, v94
	v_and_b32_e32 v89, 0xffff0000, v94
	v_pk_add_f32 v[78:79], v[90:91], v[42:43]
	v_pk_add_f32 v[76:77], v[86:87], v[40:41]
	v_lshlrev_b32_e32 v82, 16, v95
	v_and_b32_e32 v83, 0xffff0000, v95
	v_pk_add_f32 v[80:81], v[80:81], v[88:89]
	v_mul_f32_e32 v40, v77, v77
	v_mul_f32_e32 v41, v79, v79
	v_pk_add_f32 v[82:83], v[84:85], v[82:83]
	v_mul_f32_e32 v42, v81, v81
	v_fmac_f32_e32 v40, v76, v76
	v_fmac_f32_e32 v41, v78, v78
	v_mul_f32_e32 v43, v83, v83
	v_fmac_f32_e32 v42, v80, v80
	v_add_f32_e32 v40, v40, v41
	v_add_f32_e32 v40, v42, v40
	v_fmac_f32_e32 v43, v82, v82
	v_add_f32_e32 v40, v43, v40
	v_add_f32_e32 v19, v19, v40
	ds_bpermute_b32 v40, v26, v19
	global_store_dwordx4 v[96:97], v[76:79], off offset:512
	global_store_dwordx4 v[96:97], v[80:83], off offset:528
	s_waitcnt lgkmcnt(0)
	v_add_f32_e32 v19, v19, v40
	ds_bpermute_b32 v40, v27, v19
	s_and_saveexec_b64 s[24:25], s[0:1]
	s_cbranch_execz .LBB0_2055
	v_lshl_add_u64 v[24:25], v[24:25], 2, s[6:7]
	s_waitcnt lgkmcnt(0)
	v_add_f32_e32 v19, v19, v40
	global_atomic_add_f32 v[24:25], v19, off
.LBB0_2055:
	s_or_b64 exec, exec, s[24:25]
	v_add_u32_e32 v24, 0x80, v18
	v_ashrrev_i32_e32 v25, 31, v24
	s_waitcnt lgkmcnt(0)
	v_lshlrev_b64 v[40:41], 11, v[24:25]
	v_lshl_add_u64 v[76:77], v[40:41], 0, v[16:17]
	v_readlane_b32 s42, v251, 16
	v_lshlrev_b64 v[78:79], 1, v[76:77]
	v_readlane_b32 s43, v251, 17
	v_readlane_b32 s24, v251, 8
	v_readlane_b32 s28, v251, 12
	v_lshl_add_u64 v[40:41], s[42:43], 0, v[78:79]
	v_readlane_b32 s29, v251, 13
	v_or_b32_e32 v78, 0x100, v78
	v_readlane_b32 s25, v251, 9
	v_lshl_add_u64 v[80:81], v[76:77], 2, s[28:29]
	v_lshl_add_u64 v[76:77], s[42:43], 0, v[78:79]
	v_readlane_b32 s26, v251, 10
	v_readlane_b32 s27, v251, 11
	v_readlane_b32 s30, v251, 14
	v_readlane_b32 s31, v251, 15
	s_waitcnt vmcnt(23)
	s_nop 1
	v_mov_b32_e32 v40, v212
	v_mov_b32_e32 v41, v213
	v_mov_b32_e32 v42, v214
	v_mov_b32_e32 v43, v215
	v_lshlrev_b32_e32 v78, 16, v40
	v_and_b32_e32 v79, 0xffff0000, v40
	v_lshlrev_b32_e32 v40, 16, v41
	v_and_b32_e32 v41, 0xffff0000, v41
	v_lshlrev_b32_e32 v82, 16, v42
	v_and_b32_e32 v83, 0xffff0000, v42
	v_lshlrev_b32_e32 v84, 16, v43
	v_and_b32_e32 v85, 0xffff0000, v43
	v_pk_add_f32 v[42:43], v[62:63], v[40:41]
	v_pk_add_f32 v[40:41], v[60:61], v[78:79]
	v_pk_add_f32 v[62:63], v[66:67], v[84:85]
	v_pk_add_f32 v[60:61], v[72:73], v[82:83]
	global_store_dwordx4 v[80:81], v[40:43], off
	global_store_dwordx4 v[80:81], v[60:63], off offset:16
	v_mul_f32_e32 v19, v41, v41
	v_mul_f32_e32 v41, v43, v43
	v_mul_f32_e32 v43, v61, v61
	v_fmac_f32_e32 v19, v40, v40
	v_fmac_f32_e32 v41, v42, v42
	v_mul_f32_e32 v61, v63, v63
	v_fmac_f32_e32 v43, v60, v60
	v_add_f32_e32 v19, v19, v41
	v_fmac_f32_e32 v61, v62, v62
	v_add_f32_e32 v19, v43, v19
	v_add_f32_e32 v19, v61, v19
	s_waitcnt vmcnt(24)
	s_nop 1
	v_mov_b32_e32 v76, v216
	v_mov_b32_e32 v77, v217
	v_mov_b32_e32 v78, v218
	v_mov_b32_e32 v79, v219
	v_lshlrev_b32_e32 v40, 16, v76
	v_and_b32_e32 v41, 0xffff0000, v76
	v_lshlrev_b32_e32 v42, 16, v77
	v_and_b32_e32 v43, 0xffff0000, v77
	v_lshlrev_b32_e32 v72, 16, v78
	v_and_b32_e32 v73, 0xffff0000, v78
	v_pk_add_f32 v[62:63], v[74:75], v[42:43]
	v_pk_add_f32 v[60:61], v[70:71], v[40:41]
	v_lshlrev_b32_e32 v66, 16, v79
	v_and_b32_e32 v67, 0xffff0000, v79
	v_pk_add_f32 v[64:65], v[64:65], v[72:73]
	v_mul_f32_e32 v40, v61, v61
	v_mul_f32_e32 v41, v63, v63
	v_pk_add_f32 v[66:67], v[68:69], v[66:67]
	v_mul_f32_e32 v42, v65, v65
	v_fmac_f32_e32 v40, v60, v60
	v_fmac_f32_e32 v41, v62, v62
	v_mul_f32_e32 v43, v67, v67
	v_fmac_f32_e32 v42, v64, v64
	v_add_f32_e32 v40, v40, v41
	v_add_f32_e32 v40, v42, v40
	v_fmac_f32_e32 v43, v66, v66
	v_add_f32_e32 v40, v43, v40
	v_add_f32_e32 v19, v19, v40
	ds_bpermute_b32 v40, v26, v19
	global_store_dwordx4 v[80:81], v[60:63], off offset:512
	global_store_dwordx4 v[80:81], v[64:67], off offset:528
	s_waitcnt lgkmcnt(0)
	v_add_f32_e32 v19, v19, v40
	ds_bpermute_b32 v40, v27, v19
	s_and_saveexec_b64 s[24:25], s[0:1]
	s_cbranch_execz .LBB0_2057
	v_lshl_add_u64 v[24:25], v[24:25], 2, s[6:7]
	s_waitcnt lgkmcnt(0)
	v_add_f32_e32 v19, v19, v40
	global_atomic_add_f32 v[24:25], v19, off
.LBB0_2057:
	s_or_b64 exec, exec, s[24:25]
	v_add_u32_e32 v24, 0x90, v18
	v_ashrrev_i32_e32 v25, 31, v24
	s_waitcnt lgkmcnt(0)
	v_lshlrev_b64 v[40:41], 11, v[24:25]
	v_lshl_add_u64 v[60:61], v[40:41], 0, v[16:17]
	v_readlane_b32 s42, v251, 16
	v_lshlrev_b64 v[62:63], 1, v[60:61]
	v_readlane_b32 s43, v251, 17
	v_readlane_b32 s24, v251, 8
	v_readlane_b32 s28, v251, 12
	v_lshl_add_u64 v[40:41], s[42:43], 0, v[62:63]
	v_readlane_b32 s29, v251, 13
	v_or_b32_e32 v62, 0x100, v62
	v_readlane_b32 s25, v251, 9
	v_lshl_add_u64 v[64:65], v[60:61], 2, s[28:29]
	v_lshl_add_u64 v[60:61], s[42:43], 0, v[62:63]
	v_readlane_b32 s26, v251, 10
	v_readlane_b32 s27, v251, 11
	v_readlane_b32 s30, v251, 14
	v_readlane_b32 s31, v251, 15
	s_waitcnt vmcnt(25)
	s_nop 1
	v_mov_b32_e32 v40, v220
	v_mov_b32_e32 v41, v221
	v_mov_b32_e32 v42, v222
	v_mov_b32_e32 v43, v223
	v_lshlrev_b32_e32 v62, 16, v40
	v_and_b32_e32 v63, 0xffff0000, v40
	v_lshlrev_b32_e32 v40, 16, v41
	v_and_b32_e32 v41, 0xffff0000, v41
	v_lshlrev_b32_e32 v66, 16, v42
	v_and_b32_e32 v67, 0xffff0000, v42
	v_lshlrev_b32_e32 v68, 16, v43
	v_and_b32_e32 v69, 0xffff0000, v43
	v_pk_add_f32 v[42:43], v[44:45], v[40:41]
	v_pk_add_f32 v[40:41], v[46:47], v[62:63]
	v_pk_add_f32 v[46:47], v[50:51], v[68:69]
	v_pk_add_f32 v[44:45], v[56:57], v[66:67]
	global_store_dwordx4 v[64:65], v[40:43], off
	global_store_dwordx4 v[64:65], v[44:47], off offset:16
	v_mul_f32_e32 v19, v41, v41
	v_mul_f32_e32 v41, v43, v43
	v_mul_f32_e32 v43, v45, v45
	v_fmac_f32_e32 v19, v40, v40
	v_fmac_f32_e32 v41, v42, v42
	v_mul_f32_e32 v45, v47, v47
	v_fmac_f32_e32 v43, v44, v44
	v_add_f32_e32 v19, v19, v41
	v_fmac_f32_e32 v45, v46, v46
	v_add_f32_e32 v19, v43, v19
	v_add_f32_e32 v19, v45, v19
	s_waitcnt vmcnt(26)
	s_nop 1
	v_mov_b32_e32 v60, v224
	v_mov_b32_e32 v61, v225
	v_mov_b32_e32 v62, v226
	v_mov_b32_e32 v63, v227
	v_lshlrev_b32_e32 v40, 16, v60
	v_and_b32_e32 v41, 0xffff0000, v60
	v_lshlrev_b32_e32 v42, 16, v61
	v_and_b32_e32 v43, 0xffff0000, v61
	v_lshlrev_b32_e32 v46, 16, v62
	v_and_b32_e32 v47, 0xffff0000, v62
	v_pk_add_f32 v[44:45], v[58:59], v[42:43]
	v_pk_add_f32 v[42:43], v[54:55], v[40:41]
	v_lshlrev_b32_e32 v50, 16, v63
	v_and_b32_e32 v51, 0xffff0000, v63
	v_pk_add_f32 v[48:49], v[48:49], v[46:47]
	v_mul_f32_e32 v40, v43, v43
	v_mul_f32_e32 v41, v45, v45
	v_pk_add_f32 v[50:51], v[52:53], v[50:51]
	v_mul_f32_e32 v46, v49, v49
	v_fmac_f32_e32 v40, v42, v42
	v_fmac_f32_e32 v41, v44, v44
	v_mul_f32_e32 v47, v51, v51
	v_fmac_f32_e32 v46, v48, v48
	v_add_f32_e32 v40, v40, v41
	v_add_f32_e32 v40, v46, v40
	v_fmac_f32_e32 v47, v50, v50
	v_add_f32_e32 v40, v47, v40
	v_add_f32_e32 v19, v19, v40
	ds_bpermute_b32 v40, v26, v19
	global_store_dwordx4 v[64:65], v[42:45], off offset:512
	global_store_dwordx4 v[64:65], v[48:51], off offset:528
	s_waitcnt lgkmcnt(0)
	v_add_f32_e32 v19, v19, v40
	ds_bpermute_b32 v40, v27, v19
	s_and_saveexec_b64 s[24:25], s[0:1]
	s_cbranch_execz .LBB0_2059
	v_lshl_add_u64 v[24:25], v[24:25], 2, s[6:7]
	s_waitcnt lgkmcnt(0)
	v_add_f32_e32 v19, v19, v40
	global_atomic_add_f32 v[24:25], v19, off
.LBB0_2059:
	s_or_b64 exec, exec, s[24:25]
	v_add_u32_e32 v24, 0xa0, v18
	v_ashrrev_i32_e32 v25, 31, v24
	s_waitcnt lgkmcnt(0)
	v_lshlrev_b64 v[40:41], 11, v[24:25]
	v_lshl_add_u64 v[44:45], v[40:41], 0, v[16:17]
	v_readlane_b32 s42, v251, 16
	v_lshlrev_b64 v[46:47], 1, v[44:45]
	v_readlane_b32 s43, v251, 17
	v_readlane_b32 s24, v251, 8
	v_readlane_b32 s28, v251, 12
	v_lshl_add_u64 v[40:41], s[42:43], 0, v[46:47]
	v_readlane_b32 s29, v251, 13
	v_or_b32_e32 v46, 0x100, v46
	v_readlane_b32 s25, v251, 9
	v_lshl_add_u64 v[48:49], v[44:45], 2, s[28:29]
	v_lshl_add_u64 v[44:45], s[42:43], 0, v[46:47]
	v_readlane_b32 s26, v251, 10
	v_readlane_b32 s27, v251, 11
	v_readlane_b32 s30, v251, 14
	v_readlane_b32 s31, v251, 15
	s_waitcnt vmcnt(27)
	s_nop 1
	v_mov_b32_e32 v40, v228
	v_mov_b32_e32 v41, v229
	v_mov_b32_e32 v42, v230
	v_mov_b32_e32 v43, v231
	v_lshlrev_b32_e32 v46, 16, v40
	v_and_b32_e32 v47, 0xffff0000, v40
	v_lshlrev_b32_e32 v40, 16, v41
	v_and_b32_e32 v41, 0xffff0000, v41
	v_lshlrev_b32_e32 v50, 16, v42
	v_and_b32_e32 v51, 0xffff0000, v42
	v_lshlrev_b32_e32 v52, 16, v43
	v_and_b32_e32 v53, 0xffff0000, v43
	v_pk_add_f32 v[42:43], v[20:21], v[40:41]
	v_pk_add_f32 v[40:41], v[22:23], v[46:47]
	v_pk_add_f32 v[22:23], v[30:31], v[52:53]
	v_pk_add_f32 v[20:21], v[36:37], v[50:51]
	global_store_dwordx4 v[48:49], v[40:43], off
	global_store_dwordx4 v[48:49], v[20:23], off offset:16
	v_mul_f32_e32 v19, v41, v41
	v_mul_f32_e32 v30, v43, v43
	v_mul_f32_e32 v21, v21, v21
	v_fmac_f32_e32 v19, v40, v40
	v_fmac_f32_e32 v30, v42, v42
	v_mul_f32_e32 v23, v23, v23
	v_fmac_f32_e32 v21, v20, v20
	v_add_f32_e32 v19, v19, v30
	v_fmac_f32_e32 v23, v22, v22
	v_add_f32_e32 v19, v21, v19
	v_add_f32_e32 v19, v23, v19
	s_waitcnt vmcnt(28)
	s_nop 1
	v_mov_b32_e32 v44, v232
	v_mov_b32_e32 v45, v233
	v_mov_b32_e32 v46, v234
	v_mov_b32_e32 v47, v235
	v_lshlrev_b32_e32 v20, 16, v44
	v_and_b32_e32 v21, 0xffff0000, v44
	v_lshlrev_b32_e32 v22, 16, v45
	v_and_b32_e32 v23, 0xffff0000, v45
	v_lshlrev_b32_e32 v40, 16, v46
	v_and_b32_e32 v41, 0xffff0000, v46
	v_pk_add_f32 v[36:37], v[38:39], v[22:23]
	v_pk_add_f32 v[34:35], v[34:35], v[20:21]
	v_lshlrev_b32_e32 v30, 16, v47
	v_and_b32_e32 v31, 0xffff0000, v47
	v_pk_add_f32 v[28:29], v[28:29], v[40:41]
	v_mul_f32_e32 v20, v35, v35
	v_mul_f32_e32 v21, v37, v37
	v_pk_add_f32 v[30:31], v[32:33], v[30:31]
	v_mul_f32_e32 v22, v29, v29
	v_fmac_f32_e32 v20, v34, v34
	v_fmac_f32_e32 v21, v36, v36
	v_mul_f32_e32 v23, v31, v31
	v_fmac_f32_e32 v22, v28, v28
	v_add_f32_e32 v20, v20, v21
	v_add_f32_e32 v20, v22, v20
	v_fmac_f32_e32 v23, v30, v30
	v_add_f32_e32 v20, v23, v20
	v_add_f32_e32 v19, v19, v20
	ds_bpermute_b32 v20, v26, v19
	global_store_dwordx4 v[48:49], v[34:37], off offset:512
	global_store_dwordx4 v[48:49], v[28:31], off offset:528
	s_waitcnt lgkmcnt(0)
	v_add_f32_e32 v19, v19, v20
	ds_bpermute_b32 v20, v27, v19
	s_and_saveexec_b64 s[24:25], s[0:1]
	s_cbranch_execz .LBB0_2061
	v_lshl_add_u64 v[22:23], v[24:25], 2, s[6:7]
	s_waitcnt lgkmcnt(0)
	v_add_f32_e32 v19, v19, v20
	global_atomic_add_f32 v[22:23], v19, off
.LBB0_2061:
	s_or_b64 exec, exec, s[24:25]
	v_add_u32_e32 v18, 0xb0, v18
	v_ashrrev_i32_e32 v19, 31, v18
	s_waitcnt lgkmcnt(0)
	v_lshlrev_b64 v[20:21], 11, v[18:19]
	v_lshl_add_u64 v[16:17], v[20:21], 0, v[16:17]
	v_readlane_b32 s42, v251, 16
	v_lshlrev_b64 v[24:25], 1, v[16:17]
	v_readlane_b32 s43, v251, 17
	v_readlane_b32 s24, v251, 8
	v_readlane_b32 s28, v251, 12
	v_lshl_add_u64 v[20:21], s[42:43], 0, v[24:25]
	v_readlane_b32 s29, v251, 13
	v_or_b32_e32 v24, 0x100, v24
	v_lshl_add_u64 v[24:25], s[42:43], 0, v[24:25]
	v_lshl_add_u64 v[16:17], v[16:17], 2, s[28:29]
	v_readlane_b32 s25, v251, 9
	v_readlane_b32 s26, v251, 10
	v_readlane_b32 s27, v251, 11
	v_readlane_b32 s30, v251, 14
	v_readlane_b32 s31, v251, 15
	s_waitcnt vmcnt(29)
	s_nop 1
	v_mov_b32_e32 v20, v236
	v_mov_b32_e32 v21, v237
	v_mov_b32_e32 v22, v238
	v_mov_b32_e32 v23, v239
	v_lshlrev_b32_e32 v28, 16, v20
	v_and_b32_e32 v29, 0xffff0000, v20
	v_lshlrev_b32_e32 v20, 16, v21
	v_and_b32_e32 v21, 0xffff0000, v21
	v_lshlrev_b32_e32 v30, 16, v22
	v_and_b32_e32 v31, 0xffff0000, v22
	v_lshlrev_b32_e32 v32, 16, v23
	v_and_b32_e32 v33, 0xffff0000, v23
	v_pk_add_f32 v[22:23], v[8:9], v[20:21]
	v_pk_add_f32 v[20:21], v[10:11], v[28:29]
	v_pk_add_f32 v[10:11], v[12:13], v[32:33]
	v_pk_add_f32 v[8:9], v[14:15], v[30:31]
	global_store_dwordx4 v[16:17], v[20:23], off
	global_store_dwordx4 v[16:17], v[8:11], off offset:16
	v_mul_f32_e32 v21, v21, v21
	v_mul_f32_e32 v23, v23, v23
	v_mul_f32_e32 v9, v9, v9
	v_fmac_f32_e32 v21, v20, v20
	v_fmac_f32_e32 v23, v22, v22
	v_mul_f32_e32 v11, v11, v11
	v_fmac_f32_e32 v9, v8, v8
	v_add_f32_e32 v8, v21, v23
	v_fmac_f32_e32 v11, v10, v10
	v_add_f32_e32 v8, v9, v8
	v_add_f32_e32 v20, v11, v8
	s_waitcnt vmcnt(30)
	s_nop 1
	v_mov_b32_e32 v12, v240
	v_mov_b32_e32 v13, v241
	v_mov_b32_e32 v14, v242
	v_mov_b32_e32 v15, v243
	v_lshlrev_b32_e32 v8, 16, v12
	v_and_b32_e32 v9, 0xffff0000, v12
	v_lshlrev_b32_e32 v10, 16, v13
	v_and_b32_e32 v11, 0xffff0000, v13
	v_lshlrev_b32_e32 v12, 16, v14
	v_and_b32_e32 v13, 0xffff0000, v14
	v_pk_add_f32 v[6:7], v[6:7], v[10:11]
	v_pk_add_f32 v[4:5], v[4:5], v[8:9]
	v_lshlrev_b32_e32 v14, 16, v15
	v_and_b32_e32 v15, 0xffff0000, v15
	v_pk_add_f32 v[8:9], v[0:1], v[12:13]
	v_mul_f32_e32 v0, v5, v5
	v_mul_f32_e32 v1, v7, v7
	v_pk_add_f32 v[10:11], v[2:3], v[14:15]
	v_mul_f32_e32 v2, v9, v9
	v_fmac_f32_e32 v0, v4, v4
	v_fmac_f32_e32 v1, v6, v6
	v_mul_f32_e32 v3, v11, v11
	v_fmac_f32_e32 v2, v8, v8
	v_add_f32_e32 v0, v0, v1
	v_add_f32_e32 v0, v2, v0
	v_fmac_f32_e32 v3, v10, v10
	v_add_f32_e32 v0, v3, v0
	v_add_f32_e32 v0, v20, v0
	ds_bpermute_b32 v1, v26, v0
	global_store_dwordx4 v[16:17], v[4:7], off offset:512
	global_store_dwordx4 v[16:17], v[8:11], off offset:528
	s_waitcnt lgkmcnt(0)
	v_add_f32_e32 v0, v0, v1
	ds_bpermute_b32 v1, v27, v0
	s_and_saveexec_b64 s[24:25], s[0:1]
	s_cbranch_execz .LBB0_2063
	v_lshl_add_u64 v[2:3], v[18:19], 2, s[6:7]
	s_waitcnt lgkmcnt(0)
	v_add_f32_e32 v0, v0, v1
	global_atomic_add_f32 v[2:3], v0, off
